# in-GEMM: each wave owns 64 adjacent output columns (B slot mapping + epilogue), so PROJ rows are written as whole 128B lines by one wave
# baseline (speedup 1.0000x reference)
.LBB0_274:
	s_andn2_b64 vcc, exec, s[4:5]
	s_cbranch_vccnz .LBB0_273
	v_mov_b32_e32 v146, v164
	v_readlane_b32 s0, v250, 14
	v_mov_b32_e32 v1, v0
	v_readlane_b32 s49, v250, 6
	s_mov_b64 s[0:1], s[30:31]
	s_mov_b64 s[0:1], s[30:31]
	s_mov_b64 s[0:1], s[30:31]
	s_mov_b64 s[0:1], s[30:31]
	s_mov_b64 s[14:15], s[30:31]
	s_mov_b64 s[0:1], s[30:31]
	s_mov_b64 s[0:1], s[30:31]
	s_mov_b64 s[0:1], s[30:31]
	s_mov_b64 s[16:17], s[30:31]
	s_mov_b64 s[0:1], s[30:31]
	s_mov_b64 s[18:19], s[30:31]
	s_mov_b64 s[18:19], s[30:31]
	s_mov_b64 s[18:19], s[30:31]
	s_mov_b64 s[18:19], s[30:31]
	s_mov_b64 s[18:19], s[30:31]
	s_mov_b64 s[18:19], s[30:31]
	s_mov_b64 s[18:19], s[30:31]
	s_mov_b64 s[18:19], s[30:31]
	s_waitcnt vmcnt(0) lgkmcnt(0)
	v_mov_b32_e32 v10, v0
	v_readlane_b32 s18, v253, 33
	v_readlane_b32 s19, v253, 34
	s_andn2_b64 vcc, exec, s[18:19]
	v_readfirstlane_b32 s18, v10
	s_cbranch_vccnz .LBB0_295
	v_lshlrev_b32_e32 v1, 4, v10
	v_add_u32_e32 v2, 0x2000, v1
	v_ashrrev_i32_e32 v3, 31, v2
	v_lshrrev_b32_e32 v3, 22, v3
	v_add_u32_e32 v3, v2, v3
	v_ashrrev_i32_e32 v11, 10, v3
	v_mul_i32_i24_e32 v3, 0x400, v11
	v_sub_u32_e32 v2, v2, v3
	v_lshrrev_b32_e32 v3, 4, v2
	v_bitop3_b32 v2, v3, v2, 32 bitop3:0x6c
	v_ashrrev_i32_e32 v3, 31, v2
	s_add_u32 s50, s16, 0x17c00000
	v_lshrrev_b32_e32 v3, 26, v3
	s_addc_u32 s51, s17, 0
	v_add_u32_e32 v3, v2, v3
	v_lshlrev_b32_e32 v4, 3, v11
	s_add_u32 s14, s14, s12
	s_waitcnt lgkmcnt(0)
	v_ashrrev_i32_e32 v12, 6, v3
	v_and_b32_e32 v4, -16, v4
	s_addc_u32 s15, s15, s13
	v_add_u32_e32 v4, v12, v4
	s_add_u32 s52, s14, 0x1000000
	v_and_b32_e32 v5, 3, v12
	s_mov_b32 s14, 0xfffe0
	v_lshrrev_b32_e32 v6, 2, v4
	v_lshlrev_b32_e32 v7, 1, v4
	v_and_b32_e32 v3, 0xc0, v3
	v_and_or_b32 v5, v4, s14, v5
	v_and_b32_e32 v6, 4, v6
	v_and_b32_e32 v7, 24, v7
	v_sub_u32_e32 v2, v2, v3
	v_or3_b32 v5, v5, v6, v7
	v_lshlrev_b32_e32 v6, 5, v11
	v_ashrrev_i16_sdwa v2, v210, sext(v2) dst_sel:DWORD dst_unused:UNUSED_PAD src0_sel:DWORD src1_sel:BYTE_0
	v_and_b32_e32 v6, 32, v6
	v_bfe_i32 v13, v2, 0, 16
	v_add_lshl_u32 v2, v6, v13, 1
	v_lshl_add_u32 v132, v5, 12, v2
	v_lshl_add_u32 v134, v4, 12, v2
	v_bfe_i32 v2, v10, 27, 1
	v_lshrrev_b32_e32 v2, 22, v2
	v_add_u32_e32 v2, v1, v2
	v_and_b32_e32 v2, 0xfffffc00, v2
	v_sub_u32_e32 v1, v1, v2
	v_lshrrev_b32_e32 v2, 4, v1
	v_ashrrev_i32_e32 v3, 31, v10
	v_bitop3_b32 v1, v2, v1, 32 bitop3:0x6c
	v_lshrrev_b32_e32 v3, 26, v3
	v_ashrrev_i32_e32 v2, 31, v1
	v_add_u32_e32 v3, v10, v3
	v_lshrrev_b32_e32 v2, 26, v2
	v_ashrrev_i32_e32 v15, 6, v3
	v_add_u32_e32 v2, v1, v2
	v_lshlrev_b32_e32 v3, 3, v15
	v_ashrrev_i32_e32 v14, 6, v2
	v_and_b32_e32 v3, -16, v3
	v_add_u32_e32 v3, v14, v3
	v_and_b32_e32 v4, 3, v14
	v_lshrrev_b32_e32 v5, 2, v3
	v_lshlrev_b32_e32 v6, 1, v3
	v_and_b32_e32 v2, 0xc0, v2
	s_addc_u32 s53, s15, 0
	s_ashr_i32 s20, s18, 6
	v_and_or_b32 v4, v3, s14, v4
	v_and_b32_e32 v5, 4, v5
	v_and_b32_e32 v6, 24, v6
	v_sub_u32_e32 v1, v1, v2
	s_ashr_i32 s19, s18, 8
	s_lshl_b32 s54, s20, 10
	v_or3_b32 v4, v4, v5, v6
	v_lshlrev_b32_e32 v5, 5, v15
	v_ashrrev_i16_sdwa v1, v210, sext(v1) dst_sel:DWORD dst_unused:UNUSED_PAD src0_sel:DWORD src1_sel:BYTE_0
	v_readlane_b32 s14, v252, 15
	v_and_b32_e32 v5, 32, v5
	v_bfe_i32 v16, v1, 0, 16
	v_readlane_b32 s15, v252, 16
	s_add_u32 s38, s52, s14
	v_add_lshl_u32 v1, v5, v16, 1
	s_addc_u32 s39, s53, s15
	s_add_i32 s55, s54, 0
	v_lshl_add_u32 v18, v4, 12, v1
	s_lshr_b32 s100, s20, 2
	s_lshl_b32 s100, s100, 17
	v_add_u32_e32 v18, s100, v18
	s_add_i32 s101, s100, 0x40000
	v_add_u32_e32 v132, s101, v132
	s_add_i32 m0, s55, 0x10000
	v_lshl_add_u32 v136, v3, 12, v1
	global_load_lds_dwordx4 v18, s[38:39]
	s_add_i32 m0, s55, 0x12000
	s_add_u32 s14, s38, 0x20000
	global_load_lds_dwordx4 v132, s[38:39]
	s_addc_u32 s15, s39, 0
	s_add_i32 m0, s55, 0x14000
	v_mov_b32_e32 v133, v19
	global_load_lds_dwordx4 v18, s[14:15]
	s_add_i32 m0, s55, 0x16000
	v_mov_b32_e32 v137, v19
	global_load_lds_dwordx4 v132, s[14:15]
	v_readlane_b32 s14, v252, 19
	v_readlane_b32 s15, v252, 20
	s_add_u32 s40, s50, s14
	s_addc_u32 s41, s51, s15
	s_add_i32 s56, s55, 0x2000
	s_mov_b32 m0, s55
	s_add_u32 s14, s40, 0x80000
	global_load_lds_dwordx4 v136, s[40:41]
	s_mov_b32 m0, s56
	s_addc_u32 s15, s41, 0
	s_add_i32 s57, s55, 0x4000
	global_load_lds_dwordx4 v134, s[40:41]
	s_mov_b32 m0, s57
	s_add_i32 s58, s55, 0x6000
	global_load_lds_dwordx4 v136, s[14:15]
	s_mov_b32 m0, s58
	v_mov_b32_e32 v135, v19
	global_load_lds_dwordx4 v134, s[14:15]
	s_cmp_eq_u32 s19, 1
	s_mov_b32 s72, s60
	v_lshl_add_u64 v[8:9], s[38:39], 0, v[18:19]
	v_lshl_add_u64 v[6:7], s[38:39], 0, v[132:133]
	v_lshl_add_u64 v[2:3], s[40:41], 0, v[136:137]
	s_cselect_b64 s[14:15], -1, 0
	s_cmp_lg_u32 s19, 1
	v_lshl_add_u64 v[4:5], s[40:41], 0, v[134:135]
	s_cbranch_scc1 .LBB0_278
	s_barrier
.LBB0_278:
	s_add_u32 s16, s0, 0x19d00000
	s_addc_u32 s17, s1, 0
	s_lshl_b32 s0, s20, 5
	s_and_b32 s20, s0, 0x60
	s_mov_b64 s[0:1], 0x80
	s_add_i32 m0, s55, 0x18000
	v_lshl_add_u64 v[8:9], v[8:9], 0, s[0:1]
	s_waitcnt vmcnt(2)
	s_barrier
	global_load_lds_dwordx4 v[8:9], off
	v_lshl_add_u64 v[6:7], v[6:7], 0, s[0:1]
	s_add_i32 m0, s55, 0x1a000
	s_add_i32 s59, s55, 0x8000
	s_lshl_b32 s21, s19, 13
	s_lshl_b32 s22, s20, 7
	global_load_lds_dwordx4 v[6:7], off
	v_lshl_add_u64 v[2:3], v[2:3], 0, s[0:1]
	s_mov_b32 m0, s59
	s_add_i32 s60, s55, 0xa000
	global_load_lds_dwordx4 v[2:3], off
	v_lshl_add_u64 v[2:3], v[4:5], 0, s[0:1]
	s_add_u32 s0, s38, 0x20080
	s_mov_b32 m0, s60
	s_addc_u32 s1, s39, 0
	global_load_lds_dwordx4 v[2:3], off
	s_add_i32 m0, s55, 0x1c000
	v_lshl_add_u64 v[2:3], s[0:1], 0, v[18:19]
	global_load_lds_dwordx4 v[2:3], off
	v_lshl_add_u64 v[2:3], s[0:1], 0, v[132:133]
	s_add_i32 m0, s55, 0x1e000
	s_cmpk_lt_u32 s18, 0x100
	global_load_lds_dwordx4 v[2:3], off
	v_lshrrev_b32_e32 v3, 1, v10
	v_and_b32_e32 v3, 24, v3
	v_and_b32_e32 v2, 15, v10
	v_lshlrev_b32_e32 v4, 1, v3
	v_lshl_or_b32 v1, s19, 6, v2
	v_lshl_or_b32 v2, v2, 6, v4
	v_lshlrev_b32_e32 v4, 2, v10
	v_and_b32_e32 v4, 32, v4
	v_bitop3_b32 v5, v2, s21, v4 bitop3:0xde
	v_bitop3_b32 v147, v2, s22, v4 bitop3:0xde
	v_lshlrev_b32_e32 v2, 15, v11
	v_and_b32_e32 v2, 0xffff0000, v2
	v_lshl_or_b32 v148, s20, 1, v3
	v_lshl_add_u32 v2, v12, 12, v2
	v_and_b32_e32 v3, 1, v11
	v_lshl_or_b32 v2, v3, 6, v2
	v_lshl_add_u32 v138, v13, 1, v2
	v_lshlrev_b32_e32 v2, 15, v15
	v_and_b32_e32 v2, 0xffff0000, v2
	s_waitcnt vmcnt(6)
	v_lshl_add_u32 v2, v14, 12, v2
	v_and_b32_e32 v3, 1, v15
	v_lshl_or_b32 v2, v3, 6, v2
	v_readlane_b32 s0, v252, 17
	s_cselect_b64 s[18:19], -1, 0
	v_mov_b32_e32 v139, v19
	v_lshl_add_u32 v140, v16, 1, v2
	v_mov_b32_e32 v141, v19
	s_mov_b32 s61, 0
	v_add_u32_e32 v149, 0, v5
	v_readlane_b32 s62, v252, 36
	s_mov_b32 s63, s0
	s_barrier
	v_readlane_b32 s1, v252, 18
	s_branch .LBB0_281

.LBB0_288:
	s_add_u32 s40, s38, 0xfff80080
	s_addc_u32 s41, s39, -1
	s_cmp_eq_u32 s68, 28
	s_cselect_b32 s43, s23, s41
	s_cselect_b32 s42, s64, s40
	s_cselect_b32 s41, s21, s67
	s_cselect_b32 s40, s65, s66
	s_add_i32 s69, 0, 0x14000
	v_add_u32_e32 v158, s73, v147
	v_add_u32_e32 v162, s69, v147
	ds_read_b128 v[142:145], v158
	ds_read_b128 v[150:153], v158 offset:1024
	ds_read_b128 v[154:157], v158 offset:2048
	ds_read_b128 v[158:161], v158 offset:3072
	ds_read_b128 v[170:173], v162
	ds_read_b128 v[174:177], v162 offset:1024
	ds_read_b128 v[178:181], v162 offset:2048
	ds_read_b128 v[182:185], v162 offset:3072
	v_lshl_add_u64 v[162:163], s[38:39], 0, v[140:141]
	s_add_i32 m0, s55, 0xc000
	ds_read_b128 v[186:189], v149
	ds_read_b128 v[190:193], v149 offset:1024
	ds_read_b128 v[194:197], v149 offset:2048
	ds_read_b128 v[198:201], v149 offset:3072
	ds_read_b128 v[202:205], v149 offset:4096
	ds_read_b128 v[206:209], v149 offset:5120
	ds_read_b128 v[220:223], v149 offset:6144
	ds_read_b128 v[224:227], v149 offset:7168
	global_load_lds_dwordx4 v[162:163], off
	v_lshl_add_u64 v[162:163], s[38:39], 0, v[138:139]
	s_add_i32 m0, s55, 0xe000
	s_nop 0
	global_load_lds_dwordx4 v[162:163], off
	s_waitcnt vmcnt(8)
	s_waitcnt lgkmcnt(0)
	s_barrier
	s_setprio 1
	s_waitcnt lgkmcnt(0)
	v_mfma_f32_16x16x32_bf16 v[128:131], v[142:145], v[186:189], v[128:131]
	v_mfma_f32_16x16x32_bf16 v[124:127], v[154:157], v[186:189], v[124:127]
	v_mfma_f32_16x16x32_bf16 v[120:123], v[142:145], v[194:197], v[120:123]
	v_mfma_f32_16x16x32_bf16 v[112:115], v[154:157], v[194:197], v[112:115]
	v_mfma_f32_16x16x32_bf16 v[104:107], v[142:145], v[202:205], v[104:107]
	v_mfma_f32_16x16x32_bf16 v[96:99], v[154:157], v[202:205], v[96:99]
	v_mfma_f32_16x16x32_bf16 v[88:91], v[142:145], v[220:223], v[88:91]
	v_mfma_f32_16x16x32_bf16 v[80:83], v[154:157], v[220:223], v[80:83]
	v_mfma_f32_16x16x32_bf16 v[128:131], v[150:153], v[190:193], v[128:131]
	v_mfma_f32_16x16x32_bf16 v[124:127], v[158:161], v[190:193], v[124:127]
	v_mfma_f32_16x16x32_bf16 v[120:123], v[150:153], v[198:201], v[120:123]
	v_mfma_f32_16x16x32_bf16 v[112:115], v[158:161], v[198:201], v[112:115]
	v_mfma_f32_16x16x32_bf16 v[104:107], v[150:153], v[206:209], v[104:107]
	v_mfma_f32_16x16x32_bf16 v[96:99], v[158:161], v[206:209], v[96:99]
	v_mfma_f32_16x16x32_bf16 v[88:91], v[150:153], v[224:227], v[88:91]
	v_mfma_f32_16x16x32_bf16 v[80:83], v[158:161], v[224:227], v[80:83]
	s_setprio 0
	s_setprio 1
	v_mfma_f32_16x16x32_bf16 v[116:119], v[170:173], v[186:189], v[116:119]
	v_mfma_f32_16x16x32_bf16 v[108:111], v[178:181], v[186:189], v[108:111]
	v_mfma_f32_16x16x32_bf16 v[100:103], v[170:173], v[194:197], v[100:103]
	v_mfma_f32_16x16x32_bf16 v[92:95], v[178:181], v[194:197], v[92:95]
	v_mfma_f32_16x16x32_bf16 v[84:87], v[170:173], v[202:205], v[84:87]
	v_mfma_f32_16x16x32_bf16 v[76:79], v[178:181], v[202:205], v[76:79]
	v_mfma_f32_16x16x32_bf16 v[72:75], v[170:173], v[220:223], v[72:75]
	v_mfma_f32_16x16x32_bf16 v[68:71], v[178:181], v[220:223], v[68:71]
	v_mfma_f32_16x16x32_bf16 v[116:119], v[174:177], v[190:193], v[116:119]
	v_mfma_f32_16x16x32_bf16 v[108:111], v[182:185], v[190:193], v[108:111]
	v_mfma_f32_16x16x32_bf16 v[100:103], v[174:177], v[198:201], v[100:103]
	v_mfma_f32_16x16x32_bf16 v[92:95], v[182:185], v[198:201], v[92:95]
	v_mfma_f32_16x16x32_bf16 v[84:87], v[174:177], v[206:209], v[84:87]
	v_mfma_f32_16x16x32_bf16 v[76:79], v[182:185], v[206:209], v[76:79]
	v_mfma_f32_16x16x32_bf16 v[72:75], v[174:177], v[224:227], v[72:75]
	v_mfma_f32_16x16x32_bf16 v[68:71], v[182:185], v[224:227], v[68:71]
	s_setprio 0
	s_barrier
	s_add_i32 s70, s73, s54
	v_lshl_add_u64 v[162:163], s[40:41], 0, v[18:19]
	s_mov_b32 m0, s70
	ds_read_b128 v[186:189], v149 offset:16384
	ds_read_b128 v[190:193], v149 offset:17408
	ds_read_b128 v[194:197], v149 offset:18432
	ds_read_b128 v[198:201], v149 offset:19456
	ds_read_b128 v[202:205], v149 offset:20480
	ds_read_b128 v[206:209], v149 offset:21504
	ds_read_b128 v[220:223], v149 offset:22528
	ds_read_b128 v[224:227], v149 offset:23552
	global_load_lds_dwordx4 v[162:163], off
	s_add_i32 m0, s70, 0x2000
	s_add_u32 s70, s40, 0x20000
	v_lshl_add_u64 v[228:229], s[40:41], 0, v[132:133]
	s_addc_u32 s71, s41, 0
	s_add_i32 s69, s69, s54
	global_load_lds_dwordx4 v[228:229], off
	v_lshl_add_u64 v[230:231], s[70:71], 0, v[18:19]
	s_mov_b32 m0, s69
	v_lshl_add_u64 v[232:233], s[42:43], 0, v[134:135]
	global_load_lds_dwordx4 v[230:231], off
	v_lshl_add_u64 v[230:231], s[70:71], 0, v[132:133]
	s_add_i32 m0, s69, 0x2000
	s_nop 0
	global_load_lds_dwordx4 v[230:231], off
	v_lshl_add_u64 v[230:231], s[42:43], 0, v[136:137]
	s_mov_b32 m0, s55
	s_nop 0
	global_load_lds_dwordx4 v[230:231], off
	s_mov_b32 m0, s56
	s_nop 0
	global_load_lds_dwordx4 v[232:233], off
	s_waitcnt vmcnt(8)
	s_waitcnt lgkmcnt(0)
	s_barrier
	s_setprio 1
	s_waitcnt lgkmcnt(0)
	v_mfma_f32_16x16x32_bf16 v[64:67], v[142:145], v[186:189], v[64:67]
	v_mfma_f32_16x16x32_bf16 v[60:63], v[154:157], v[186:189], v[60:63]
	v_mfma_f32_16x16x32_bf16 v[56:59], v[142:145], v[194:197], v[56:59]
	v_mfma_f32_16x16x32_bf16 v[48:51], v[154:157], v[194:197], v[48:51]
	v_mfma_f32_16x16x32_bf16 v[40:43], v[142:145], v[202:205], v[40:43]
	v_mfma_f32_16x16x32_bf16 v[32:35], v[154:157], v[202:205], v[32:35]
	v_mfma_f32_16x16x32_bf16 v[24:27], v[142:145], v[220:223], v[24:27]
	v_mfma_f32_16x16x32_bf16 v[14:17], v[154:157], v[220:223], v[14:17]
	v_mfma_f32_16x16x32_bf16 v[64:67], v[150:153], v[190:193], v[64:67]
	v_mfma_f32_16x16x32_bf16 v[60:63], v[158:161], v[190:193], v[60:63]
	v_mfma_f32_16x16x32_bf16 v[56:59], v[150:153], v[198:201], v[56:59]
	v_mfma_f32_16x16x32_bf16 v[48:51], v[158:161], v[198:201], v[48:51]
	v_mfma_f32_16x16x32_bf16 v[40:43], v[150:153], v[206:209], v[40:43]
	v_mfma_f32_16x16x32_bf16 v[32:35], v[158:161], v[206:209], v[32:35]
	v_mfma_f32_16x16x32_bf16 v[24:27], v[150:153], v[224:227], v[24:27]
	v_mfma_f32_16x16x32_bf16 v[14:17], v[158:161], v[224:227], v[14:17]
	s_setprio 0
	s_setprio 1
	v_mfma_f32_16x16x32_bf16 v[52:55], v[170:173], v[186:189], v[52:55]
	v_mfma_f32_16x16x32_bf16 v[44:47], v[178:181], v[186:189], v[44:47]
	v_mfma_f32_16x16x32_bf16 v[36:39], v[170:173], v[194:197], v[36:39]
	v_mfma_f32_16x16x32_bf16 v[28:31], v[178:181], v[194:197], v[28:31]
	v_mfma_f32_16x16x32_bf16 v[20:23], v[170:173], v[202:205], v[20:23]
	v_mfma_f32_16x16x32_bf16 v[10:13], v[178:181], v[202:205], v[10:13]
	v_mfma_f32_16x16x32_bf16 v[6:9], v[170:173], v[220:223], v[6:9]
	v_mfma_f32_16x16x32_bf16 v[2:5], v[178:181], v[220:223], v[2:5]
	v_mfma_f32_16x16x32_bf16 v[52:55], v[174:177], v[190:193], v[52:55]
	v_mfma_f32_16x16x32_bf16 v[44:47], v[182:185], v[190:193], v[44:47]
	v_mfma_f32_16x16x32_bf16 v[36:39], v[174:177], v[198:201], v[36:39]
	v_mfma_f32_16x16x32_bf16 v[28:31], v[182:185], v[198:201], v[28:31]
	v_mfma_f32_16x16x32_bf16 v[20:23], v[174:177], v[206:209], v[20:23]
	v_mfma_f32_16x16x32_bf16 v[10:13], v[182:185], v[206:209], v[10:13]
	v_mfma_f32_16x16x32_bf16 v[6:9], v[174:177], v[224:227], v[6:9]
	v_mfma_f32_16x16x32_bf16 v[2:5], v[182:185], v[224:227], v[2:5]
	s_setprio 0
	s_barrier
	s_add_i32 s69, 0, 0x18000
	s_add_i32 s70, 0, 0x1c000
	v_add_u32_e32 v158, s69, v147
	v_add_u32_e32 v167, s70, v147
	ds_read_b128 v[142:145], v158
	ds_read_b128 v[150:153], v158 offset:1024
	ds_read_b128 v[154:157], v158 offset:2048
	ds_read_b128 v[158:161], v158 offset:3072
	ds_read_b128 v[170:173], v167
	ds_read_b128 v[174:177], v167 offset:1024
	ds_read_b128 v[178:181], v167 offset:2048
	ds_read_b128 v[182:185], v167 offset:3072
	s_add_u32 s42, s42, 0x80000
	s_addc_u32 s43, s43, 0
	s_mov_b32 m0, s57
	v_lshl_add_u64 v[234:235], s[42:43], 0, v[136:137]
	ds_read_b128 v[186:189], v149 offset:32768
	ds_read_b128 v[190:193], v149 offset:33792
	ds_read_b128 v[194:197], v149 offset:34816
	ds_read_b128 v[198:201], v149 offset:35840
	ds_read_b128 v[202:205], v149 offset:36864
	ds_read_b128 v[206:209], v149 offset:37888
	ds_read_b128 v[220:223], v149 offset:38912
	ds_read_b128 v[224:227], v149 offset:39936
	global_load_lds_dwordx4 v[234:235], off
	v_lshl_add_u64 v[234:235], s[42:43], 0, v[134:135]
	s_mov_b32 m0, s58
	s_nop 0
	global_load_lds_dwordx4 v[234:235], off
	s_waitcnt vmcnt(8)
	s_waitcnt lgkmcnt(0)
	s_barrier
	s_setprio 1
	s_waitcnt lgkmcnt(0)
	v_mfma_f32_16x16x32_bf16 v[128:131], v[142:145], v[186:189], v[128:131]
	v_mfma_f32_16x16x32_bf16 v[124:127], v[154:157], v[186:189], v[124:127]
	v_mfma_f32_16x16x32_bf16 v[120:123], v[142:145], v[194:197], v[120:123]
	v_mfma_f32_16x16x32_bf16 v[112:115], v[154:157], v[194:197], v[112:115]
	v_mfma_f32_16x16x32_bf16 v[104:107], v[142:145], v[202:205], v[104:107]
	v_mfma_f32_16x16x32_bf16 v[96:99], v[154:157], v[202:205], v[96:99]
	v_mfma_f32_16x16x32_bf16 v[88:91], v[142:145], v[220:223], v[88:91]
	v_mfma_f32_16x16x32_bf16 v[80:83], v[154:157], v[220:223], v[80:83]
	v_mfma_f32_16x16x32_bf16 v[128:131], v[150:153], v[190:193], v[128:131]
	v_mfma_f32_16x16x32_bf16 v[124:127], v[158:161], v[190:193], v[124:127]
	v_mfma_f32_16x16x32_bf16 v[120:123], v[150:153], v[198:201], v[120:123]
	v_mfma_f32_16x16x32_bf16 v[112:115], v[158:161], v[198:201], v[112:115]
	v_mfma_f32_16x16x32_bf16 v[104:107], v[150:153], v[206:209], v[104:107]
	v_mfma_f32_16x16x32_bf16 v[96:99], v[158:161], v[206:209], v[96:99]
	v_mfma_f32_16x16x32_bf16 v[88:91], v[150:153], v[224:227], v[88:91]
	v_mfma_f32_16x16x32_bf16 v[80:83], v[158:161], v[224:227], v[80:83]
	s_setprio 0
	s_setprio 1
	v_mfma_f32_16x16x32_bf16 v[116:119], v[170:173], v[186:189], v[116:119]
	v_mfma_f32_16x16x32_bf16 v[108:111], v[178:181], v[186:189], v[108:111]
	v_mfma_f32_16x16x32_bf16 v[100:103], v[170:173], v[194:197], v[100:103]
	v_mfma_f32_16x16x32_bf16 v[92:95], v[178:181], v[194:197], v[92:95]
	v_mfma_f32_16x16x32_bf16 v[84:87], v[170:173], v[202:205], v[84:87]
	v_mfma_f32_16x16x32_bf16 v[76:79], v[178:181], v[202:205], v[76:79]
	v_mfma_f32_16x16x32_bf16 v[72:75], v[170:173], v[220:223], v[72:75]
	v_mfma_f32_16x16x32_bf16 v[68:71], v[178:181], v[220:223], v[68:71]
	v_mfma_f32_16x16x32_bf16 v[116:119], v[174:177], v[190:193], v[116:119]
	v_mfma_f32_16x16x32_bf16 v[108:111], v[182:185], v[190:193], v[108:111]
	v_mfma_f32_16x16x32_bf16 v[100:103], v[174:177], v[198:201], v[100:103]
	v_mfma_f32_16x16x32_bf16 v[92:95], v[182:185], v[198:201], v[92:95]
	v_mfma_f32_16x16x32_bf16 v[84:87], v[174:177], v[206:209], v[84:87]
	v_mfma_f32_16x16x32_bf16 v[76:79], v[182:185], v[206:209], v[76:79]
	v_mfma_f32_16x16x32_bf16 v[72:75], v[174:177], v[224:227], v[72:75]
	v_mfma_f32_16x16x32_bf16 v[68:71], v[182:185], v[224:227], v[68:71]
	s_setprio 0
	s_barrier
	s_add_i32 s42, s69, s54
	v_lshl_add_u64 v[162:163], v[162:163], 0, s[74:75]
	s_mov_b32 m0, s42
	ds_read_b128 v[186:189], v149 offset:49152
	ds_read_b128 v[190:193], v149 offset:50176
	ds_read_b128 v[194:197], v149 offset:51200
	ds_read_b128 v[198:201], v149 offset:52224
	ds_read_b128 v[202:205], v149 offset:53248
	ds_read_b128 v[206:209], v149 offset:54272
	ds_read_b128 v[220:223], v149 offset:55296
	ds_read_b128 v[224:227], v149 offset:56320
	global_load_lds_dwordx4 v[162:163], off
	s_add_i32 m0, s42, 0x2000
	s_add_u32 s40, s40, 0x20080
	v_lshl_add_u64 v[162:163], v[228:229], 0, s[74:75]
	s_addc_u32 s41, s41, 0
	s_add_i32 s42, s70, s54
	global_load_lds_dwordx4 v[162:163], off
	v_lshl_add_u64 v[162:163], s[40:41], 0, v[18:19]
	s_mov_b32 m0, s42
	s_nop 0
	global_load_lds_dwordx4 v[162:163], off
	v_lshl_add_u64 v[162:163], s[40:41], 0, v[132:133]
	s_add_i32 m0, s42, 0x2000
	s_nop 0
	global_load_lds_dwordx4 v[162:163], off
	v_lshl_add_u64 v[162:163], v[230:231], 0, s[74:75]
	s_mov_b32 m0, s59
	s_nop 0
	global_load_lds_dwordx4 v[162:163], off
	v_lshl_add_u64 v[162:163], v[232:233], 0, s[74:75]
	s_mov_b32 m0, s60
	s_nop 0
	global_load_lds_dwordx4 v[162:163], off
	s_waitcnt vmcnt(8)
	s_waitcnt lgkmcnt(0)
	s_barrier
	s_setprio 1
	s_waitcnt lgkmcnt(0)
	v_mfma_f32_16x16x32_bf16 v[64:67], v[142:145], v[186:189], v[64:67]
	v_mfma_f32_16x16x32_bf16 v[60:63], v[154:157], v[186:189], v[60:63]
	v_mfma_f32_16x16x32_bf16 v[56:59], v[142:145], v[194:197], v[56:59]
	v_mfma_f32_16x16x32_bf16 v[48:51], v[154:157], v[194:197], v[48:51]
	v_mfma_f32_16x16x32_bf16 v[40:43], v[142:145], v[202:205], v[40:43]
	v_mfma_f32_16x16x32_bf16 v[32:35], v[154:157], v[202:205], v[32:35]
	v_mfma_f32_16x16x32_bf16 v[24:27], v[142:145], v[220:223], v[24:27]
	v_mfma_f32_16x16x32_bf16 v[14:17], v[154:157], v[220:223], v[14:17]
	v_mfma_f32_16x16x32_bf16 v[64:67], v[150:153], v[190:193], v[64:67]
	v_mfma_f32_16x16x32_bf16 v[60:63], v[158:161], v[190:193], v[60:63]
	v_mfma_f32_16x16x32_bf16 v[56:59], v[150:153], v[198:201], v[56:59]
	v_mfma_f32_16x16x32_bf16 v[48:51], v[158:161], v[198:201], v[48:51]
	v_mfma_f32_16x16x32_bf16 v[40:43], v[150:153], v[206:209], v[40:43]
	v_mfma_f32_16x16x32_bf16 v[32:35], v[158:161], v[206:209], v[32:35]
	v_mfma_f32_16x16x32_bf16 v[24:27], v[150:153], v[224:227], v[24:27]
	v_mfma_f32_16x16x32_bf16 v[14:17], v[158:161], v[224:227], v[14:17]
	s_setprio 0
	s_setprio 1
	v_mfma_f32_16x16x32_bf16 v[52:55], v[170:173], v[186:189], v[52:55]
	v_mfma_f32_16x16x32_bf16 v[44:47], v[178:181], v[186:189], v[44:47]
	v_mfma_f32_16x16x32_bf16 v[36:39], v[170:173], v[194:197], v[36:39]
	v_mfma_f32_16x16x32_bf16 v[28:31], v[178:181], v[194:197], v[28:31]
	v_mfma_f32_16x16x32_bf16 v[20:23], v[170:173], v[202:205], v[20:23]
	v_mfma_f32_16x16x32_bf16 v[10:13], v[178:181], v[202:205], v[10:13]
	v_mfma_f32_16x16x32_bf16 v[6:9], v[170:173], v[220:223], v[6:9]
	v_mfma_f32_16x16x32_bf16 v[2:5], v[178:181], v[220:223], v[2:5]
	v_mfma_f32_16x16x32_bf16 v[52:55], v[174:177], v[190:193], v[52:55]
	v_mfma_f32_16x16x32_bf16 v[44:47], v[182:185], v[190:193], v[44:47]
	v_mfma_f32_16x16x32_bf16 v[36:39], v[174:177], v[198:201], v[36:39]
	v_mfma_f32_16x16x32_bf16 v[28:31], v[182:185], v[198:201], v[28:31]
	v_mfma_f32_16x16x32_bf16 v[20:23], v[174:177], v[206:209], v[20:23]
	v_mfma_f32_16x16x32_bf16 v[10:13], v[182:185], v[206:209], v[10:13]
	v_mfma_f32_16x16x32_bf16 v[6:9], v[174:177], v[224:227], v[6:9]
	v_mfma_f32_16x16x32_bf16 v[2:5], v[182:185], v[224:227], v[2:5]
	s_setprio 0
	s_barrier
	s_add_i32 s68, s68, 2
	s_add_u32 s66, s66, 0x100
	s_addc_u32 s67, s67, 0
	s_add_u32 s38, s38, 0x100
	s_addc_u32 s39, s39, 0
	s_cmp_gt_u32 s68, 29
	s_cbranch_scc0 .LBB0_288
	s_and_b64 vcc, exec, s[18:19]
	s_cbranch_vccz .LBB0_291
	s_barrier
.LBB0_291:
	v_lshl_or_b32 v144, s62, 8, v148
	v_lshl_add_u32 v152, s63, 8, v1
	v_ashrrev_i32_e32 v145, 31, v144
	v_mov_b64_e32 v[142:143], s[16:17]
	v_mad_i64_i32 v[150:151], s[38:39], v152, s33, v[142:143]
	v_lshlrev_b64 v[144:145], 1, v[144:145]
	v_lshl_add_u64 v[150:151], v[150:151], 0, v[144:145]
	v_cvt_pk_bf16_f32 v128, v128, v129
	v_cvt_pk_bf16_f32 v129, v130, v131
	v_cvt_pk_bf16_f32 v130, v124, v125
	v_cvt_pk_bf16_f32 v131, v126, v127
	global_store_dwordx4 v[150:151], v[128:131], off
	v_cvt_pk_bf16_f32 v116, v116, v117
	v_cvt_pk_bf16_f32 v117, v118, v119
	v_cvt_pk_bf16_f32 v118, v108, v109
	v_or_b32_e32 v108, 16, v152
	v_mad_i64_i32 v[108:109], s[38:39], v108, s33, v[142:143]
	v_cvt_pk_bf16_f32 v119, v110, v111
	global_store_dwordx4 v[150:151], v[116:119], off offset:64
	s_andn2_b64 vcc, exec, s[0:1]
	s_mov_b64 s[0:1], -1
	v_lshl_add_u64 v[116:117], v[108:109], 0, v[144:145]
	v_cvt_pk_bf16_f32 v108, v120, v121
	v_cvt_pk_bf16_f32 v109, v122, v123
	v_cvt_pk_bf16_f32 v110, v112, v113
	v_cvt_pk_bf16_f32 v111, v114, v115
	global_store_dwordx4 v[116:117], v[108:111], off
	v_cvt_pk_bf16_f32 v100, v100, v101
	v_cvt_pk_bf16_f32 v101, v102, v103
	v_cvt_pk_bf16_f32 v102, v92, v93
	v_or_b32_e32 v92, 32, v152
	v_mad_i64_i32 v[92:93], s[38:39], v92, s33, v[142:143]
	v_cvt_pk_bf16_f32 v103, v94, v95
	global_store_dwordx4 v[116:117], v[100:103], off offset:64
	s_nop 1
	v_lshl_add_u64 v[100:101], v[92:93], 0, v[144:145]
	v_cvt_pk_bf16_f32 v92, v104, v105
	v_cvt_pk_bf16_f32 v93, v106, v107
	v_cvt_pk_bf16_f32 v94, v96, v97
	v_cvt_pk_bf16_f32 v95, v98, v99
	global_store_dwordx4 v[100:101], v[92:95], off
	v_cvt_pk_bf16_f32 v84, v84, v85
	v_cvt_pk_bf16_f32 v85, v86, v87
	v_cvt_pk_bf16_f32 v86, v76, v77
	v_or_b32_e32 v76, 48, v152
	v_mad_i64_i32 v[76:77], s[38:39], v76, s33, v[142:143]
	v_cvt_pk_bf16_f32 v87, v78, v79
	global_store_dwordx4 v[100:101], v[84:87], off offset:64
	s_nop 1
	v_lshl_add_u64 v[84:85], v[76:77], 0, v[144:145]
	v_cvt_pk_bf16_f32 v76, v88, v89
	v_cvt_pk_bf16_f32 v77, v90, v91
	v_cvt_pk_bf16_f32 v78, v80, v81
	v_cvt_pk_bf16_f32 v79, v82, v83
	global_store_dwordx4 v[84:85], v[76:79], off
	v_cvt_pk_bf16_f32 v72, v72, v73
	v_cvt_pk_bf16_f32 v73, v74, v75
	v_cvt_pk_bf16_f32 v74, v68, v69
	v_add_u32_e32 v68, 0x80, v152
	v_mad_i64_i32 v[68:69], s[38:39], v68, s33, v[142:143]
	v_lshl_add_u64 v[68:69], v[68:69], 0, v[144:145]
	v_cvt_pk_bf16_f32 v75, v70, v71
	global_store_dwordx4 v[84:85], v[72:75], off offset:64
	v_cvt_pk_bf16_f32 v64, v64, v65
	v_cvt_pk_bf16_f32 v65, v66, v67
	v_cvt_pk_bf16_f32 v66, v60, v61
	v_cvt_pk_bf16_f32 v67, v62, v63
	global_store_dwordx4 v[68:69], v[64:67], off
	v_cvt_pk_bf16_f32 v52, v52, v53
	v_cvt_pk_bf16_f32 v53, v54, v55
	v_cvt_pk_bf16_f32 v54, v44, v45
	v_add_u32_e32 v44, 0x90, v152
	v_mad_i64_i32 v[44:45], s[38:39], v44, s33, v[142:143]
	v_cvt_pk_bf16_f32 v55, v46, v47
	global_store_dwordx4 v[68:69], v[52:55], off offset:64
	s_nop 1
	v_lshl_add_u64 v[52:53], v[44:45], 0, v[144:145]
	v_cvt_pk_bf16_f32 v44, v56, v57
	v_cvt_pk_bf16_f32 v45, v58, v59
	v_cvt_pk_bf16_f32 v46, v48, v49
	v_cvt_pk_bf16_f32 v47, v50, v51
	global_store_dwordx4 v[52:53], v[44:47], off
	v_cvt_pk_bf16_f32 v36, v36, v37
	v_cvt_pk_bf16_f32 v37, v38, v39
	v_cvt_pk_bf16_f32 v38, v28, v29
	v_add_u32_e32 v28, 0xa0, v152
	v_mad_i64_i32 v[28:29], s[38:39], v28, s33, v[142:143]
	v_cvt_pk_bf16_f32 v39, v30, v31
	global_store_dwordx4 v[52:53], v[36:39], off offset:64
	s_nop 1
	v_lshl_add_u64 v[36:37], v[28:29], 0, v[144:145]
	v_cvt_pk_bf16_f32 v28, v40, v41
	v_cvt_pk_bf16_f32 v29, v42, v43
	v_cvt_pk_bf16_f32 v30, v32, v33
	v_cvt_pk_bf16_f32 v31, v34, v35
	global_store_dwordx4 v[36:37], v[28:31], off
	v_cvt_pk_bf16_f32 v20, v20, v21
	v_cvt_pk_bf16_f32 v21, v22, v23
	v_cvt_pk_bf16_f32 v22, v10, v11
	v_add_u32_e32 v10, 0xb0, v152
	v_mad_i64_i32 v[10:11], s[38:39], v10, s33, v[142:143]
	v_cvt_pk_bf16_f32 v23, v12, v13
	global_store_dwordx4 v[36:37], v[20:23], off offset:64
	s_nop 1
	v_lshl_add_u64 v[20:21], v[10:11], 0, v[144:145]
	v_cvt_pk_bf16_f32 v10, v24, v25
	v_cvt_pk_bf16_f32 v11, v26, v27
	v_cvt_pk_bf16_f32 v12, v14, v15
	v_cvt_pk_bf16_f32 v13, v16, v17
	global_store_dwordx4 v[20:21], v[10:13], off
	v_cvt_pk_bf16_f32 v6, v6, v7
	v_cvt_pk_bf16_f32 v7, v8, v9
	v_cvt_pk_bf16_f32 v8, v2, v3
	v_cvt_pk_bf16_f32 v9, v4, v5
	global_store_dwordx4 v[20:21], v[6:9], off offset:64
	s_cbranch_vccnz .LBB0_280
	s_andn2_b64 vcc, exec, s[14:15]
	s_cbranch_vccnz .LBB0_279
	s_barrier
	s_branch .LBB0_279
